# v97 + attention row-max chain: removed fmax self-canonicalisations (max(x,x)) around the permlane swap and merged the chain head; same in P4 softmax
# speedup vs baseline: 1.0042x; 1.0042x over previous
.LBB0_272:
	v_add_u32_e32 v197, s62, v240
	ds_read_b64_tr_b16 v[188:189], v197 offset:24576
	ds_read_b64_tr_b16 v[190:191], v197 offset:25088
	s_waitcnt lgkmcnt(11)
	v_mfma_f32_32x32x16_bf16 v[80:95], v[184:187], v[128:131], 0
	v_add_f32_e32 v64, v48, v49
	v_add_f32_e32 v64, v50, v64
	v_add_f32_e32 v64, v51, v64
	v_add_f32_e32 v64, v52, v64
	v_add_f32_e32 v64, v53, v64
	v_cvt_pk_bf16_f32 v144, v48, v49
	v_cvt_pk_bf16_f32 v145, v50, v51
	ds_read_b64_tr_b16 v[184:185], v197 offset:28672
	ds_read_b64_tr_b16 v[186:187], v197 offset:29184
	v_add_f32_e32 v48, v54, v64
	s_waitcnt lgkmcnt(12)
	v_mfma_f32_32x32x16_bf16 v[64:79], v[176:179], v[128:131], 0
	v_add_f32_e32 v48, v55, v48
	v_add_f32_e32 v48, v56, v48
	v_add_f32_e32 v132, v57, v48
	v_cvt_pk_bf16_f32 v146, v52, v53
	v_cvt_pk_bf16_f32 v147, v54, v55
	ds_read_b64_tr_b16 v[48:49], v197 offset:25600
	ds_read_b64_tr_b16 v[50:51], v197 offset:26112
	s_waitcnt lgkmcnt(11)
	v_mfma_f32_32x32x16_bf16 v[80:95], v[180:183], v[124:127], v[80:95]
	v_add_f32_e32 v52, v58, v132
	v_add_f32_e32 v52, v59, v52
	v_add_f32_e32 v52, v60, v52
	v_add_f32_e32 v132, v61, v52
	v_cvt_pk_bf16_f32 v140, v56, v57
	v_cvt_pk_bf16_f32 v141, v58, v59
	ds_read_b64_tr_b16 v[52:53], v197 offset:29696
	ds_read_b64_tr_b16 v[54:55], v197 offset:30208
	s_waitcnt lgkmcnt(12)
	v_mfma_f32_32x32x16_bf16 v[64:79], v[172:175], v[124:127], v[64:79]
	v_add_f32_e32 v56, v62, v132
	v_add_f32_e32 v56, v63, v56
	v_add_f32_e32 v56, v32, v56
	v_add_f32_e32 v132, v33, v56
	v_cvt_pk_bf16_f32 v142, v60, v61
	v_cvt_pk_bf16_f32 v143, v62, v63
	ds_read_b64_tr_b16 v[56:57], v197 offset:26624
	ds_read_b64_tr_b16 v[58:59], v197 offset:27136
	s_waitcnt lgkmcnt(13)
	v_mfma_f32_32x32x16_bf16 v[80:95], v[168:171], v[120:123], v[80:95]
	v_add_f32_e32 v60, v34, v132
	v_add_f32_e32 v60, v35, v60
	v_add_f32_e32 v60, v36, v60
	v_add_f32_e32 v60, v37, v60
	v_cvt_pk_bf16_f32 v136, v32, v33
	v_cvt_pk_bf16_f32 v137, v34, v35
	ds_read_b64_tr_b16 v[32:33], v197 offset:30720
	ds_read_b64_tr_b16 v[34:35], v197 offset:31232
	s_waitcnt lgkmcnt(14)
	v_mfma_f32_32x32x16_bf16 v[64:79], v[164:167], v[120:123], v[64:79]
	v_add_f32_e32 v60, v38, v60
	v_add_f32_e32 v60, v39, v60
	v_add_f32_e32 v60, v40, v60
	v_add_f32_e32 v60, v41, v60
	v_cvt_pk_bf16_f32 v138, v36, v37
	v_cvt_pk_bf16_f32 v139, v38, v39
	ds_read_b64_tr_b16 v[36:37], v197 offset:27648
	ds_read_b64_tr_b16 v[38:39], v197 offset:28160
	s_waitcnt lgkmcnt(14)
	v_mfma_f32_32x32x16_bf16 v[80:95], v[160:163], v[116:119], v[80:95]
	v_add_f32_e32 v60, v42, v60
	v_add_f32_e32 v60, v43, v60
	v_add_f32_e32 v60, v44, v60
	v_add_f32_e32 v60, v45, v60
	v_cvt_pk_bf16_f32 v132, v40, v41
	v_cvt_pk_bf16_f32 v133, v42, v43
	ds_read_b64_tr_b16 v[40:41], v197 offset:31744
	ds_read_b64_tr_b16 v[42:43], v197 offset:32256
	v_mfma_f32_32x32x16_bf16 v[64:79], v[156:159], v[116:119], v[64:79]
	v_add_f32_e32 v60, v46, v60
	v_add_f32_e32 v60, v47, v60
	v_add_f32_e32 v60, 0, v60
	v_cvt_pk_bf16_f32 v134, v44, v45
	v_cvt_pk_bf16_f32 v135, v46, v47
	v_mfma_f32_32x32x16_bf16 v[80:95], v[152:155], v[96:99], v[80:95]
	v_lshl_add_u64 v[214:215], v[212:213], 0, s[20:21]
	v_lshl_add_u64 v[44:45], v[214:215], 0, s[28:29]
	v_lshl_add_u64 v[216:217], v[198:199], 0, s[20:21]
	s_add_i32 s43, s68, s97
	s_mov_b32 s46, m0
	s_mov_b32 m0, s43
	s_nop 0
	global_load_lds_dwordx4 v[44:45], off
	s_mov_b32 m0, s46
	v_lshl_add_u64 v[44:45], v[216:217], 0, s[30:31]
	s_add_i32 s43, s47, s70
	v_mfma_f32_32x32x16_bf16 v[64:79], v[148:151], v[96:99], v[64:79]
	s_mov_b32 s46, m0
	s_mov_b32 m0, s43
	s_nop 0
	global_load_lds_dwordx4 v[44:45], off
	s_mov_b32 m0, s46
	s_nop 4
	v_max_f32_e32 v44, v80, v81
	v_add_f32_e32 v197, v243, v60
	s_nop 2
	v_max3_f32 v45, v82, v83, v65
	v_max3_f32 v44, v44, v64, v66
	v_max3_f32 v44, v44, v67, v84
	v_max3_f32 v45, v45, v86, v87
	v_max3_f32 v44, v44, v85, v68
	v_max3_f32 v45, v45, v70, v71
	v_max3_f32 v44, v44, v69, v88
	v_max3_f32 v45, v45, v90, v91
	v_max3_f32 v44, v44, v89, v72
	v_max3_f32 v45, v45, v74, v75
	v_max3_f32 v44, v44, v73, v92
	v_max3_f32 v45, v45, v94, v95
	v_max3_f32 v44, v44, v93, v76
	v_max3_f32 v45, v45, v78, v79
	v_max3_f32 v44, v44, v77, v45
	v_mov_b32_e32 v45, v44
	s_nop 1
	v_permlane32_swap_b32_e32 v44, v45
	v_max_f32_e32 v44, v44, v45
	v_cmp_lt_f32_e32 vcc, s84, v44
	s_cmp_lg_u64 vcc, 0
	s_cselect_b64 s[62:63], -1, 0
	s_cbranch_vccnz .LBB0_280

.LBB0_275:
	s_add_i32 s43, s47, 0x2000
	s_cmpk_lg_i32 s47, 0x4000
	s_cselect_b32 s43, s43, 0
	v_add_u32_e32 v190, s68, v240
	ds_read_b64_tr_b16 v[160:161], v190 offset:24576
	ds_read_b64_tr_b16 v[162:163], v190 offset:25088
	s_waitcnt lgkmcnt(11)
	v_mfma_f32_32x32x16_bf16 v[48:63], v[60:63], v[128:131], 0
	v_add_f32_e32 v32, v80, v81
	v_add_f32_e32 v32, v82, v32
	v_add_f32_e32 v32, v83, v32
	v_add_f32_e32 v32, v84, v32
	v_add_f32_e32 v32, v85, v32
	v_cvt_pk_bf16_f32 v144, v80, v81
	v_cvt_pk_bf16_f32 v145, v82, v83
	ds_read_b64_tr_b16 v[156:157], v190 offset:28672
	ds_read_b64_tr_b16 v[158:159], v190 offset:29184
	v_add_f32_e32 v32, v86, v32
	v_add_f32_e32 v32, v87, v32
	v_add_f32_e32 v32, v88, v32
	v_add_f32_e32 v132, v89, v32
	s_waitcnt lgkmcnt(12)
	v_mfma_f32_32x32x16_bf16 v[32:47], v[44:47], v[128:131], 0
	v_cvt_pk_bf16_f32 v146, v84, v85
	v_cvt_pk_bf16_f32 v147, v86, v87
	ds_read_b64_tr_b16 v[80:81], v190 offset:25600
	ds_read_b64_tr_b16 v[82:83], v190 offset:26112
	s_waitcnt lgkmcnt(11)
	v_mfma_f32_32x32x16_bf16 v[48:63], v[184:187], v[124:127], v[48:63]
	v_add_f32_e32 v84, v90, v132
	v_add_f32_e32 v84, v91, v84
	v_add_f32_e32 v84, v92, v84
	v_add_f32_e32 v132, v93, v84
	v_cvt_pk_bf16_f32 v140, v88, v89
	v_cvt_pk_bf16_f32 v141, v90, v91
	ds_read_b64_tr_b16 v[84:85], v190 offset:29696
	ds_read_b64_tr_b16 v[86:87], v190 offset:30208
	s_waitcnt lgkmcnt(12)
	v_mfma_f32_32x32x16_bf16 v[32:47], v[180:183], v[124:127], v[32:47]
	v_add_f32_e32 v88, v94, v132
	v_add_f32_e32 v88, v95, v88
	v_add_f32_e32 v88, v64, v88
	v_add_f32_e32 v132, v65, v88
	v_cvt_pk_bf16_f32 v142, v92, v93
	v_cvt_pk_bf16_f32 v143, v94, v95
	ds_read_b64_tr_b16 v[88:89], v190 offset:26624
	ds_read_b64_tr_b16 v[90:91], v190 offset:27136
	s_waitcnt lgkmcnt(13)
	v_mfma_f32_32x32x16_bf16 v[48:63], v[176:179], v[120:123], v[48:63]
	v_add_f32_e32 v92, v66, v132
	v_add_f32_e32 v92, v67, v92
	v_add_f32_e32 v92, v68, v92
	v_add_f32_e32 v92, v69, v92
	v_cvt_pk_bf16_f32 v136, v64, v65
	v_cvt_pk_bf16_f32 v137, v66, v67
	ds_read_b64_tr_b16 v[64:65], v190 offset:30720
	ds_read_b64_tr_b16 v[66:67], v190 offset:31232
	s_waitcnt lgkmcnt(14)
	v_mfma_f32_32x32x16_bf16 v[32:47], v[172:175], v[120:123], v[32:47]
	v_add_f32_e32 v92, v70, v92
	v_add_f32_e32 v92, v71, v92
	v_add_f32_e32 v92, v72, v92
	v_add_f32_e32 v92, v73, v92
	v_cvt_pk_bf16_f32 v138, v68, v69
	v_cvt_pk_bf16_f32 v139, v70, v71
	ds_read_b64_tr_b16 v[68:69], v190 offset:27648
	ds_read_b64_tr_b16 v[70:71], v190 offset:28160
	s_waitcnt lgkmcnt(14)
	v_mfma_f32_32x32x16_bf16 v[48:63], v[168:171], v[116:119], v[48:63]
	v_add_f32_e32 v92, v74, v92
	v_add_f32_e32 v92, v75, v92
	v_add_f32_e32 v92, v76, v92
	v_add_f32_e32 v92, v77, v92
	v_cvt_pk_bf16_f32 v132, v72, v73
	v_cvt_pk_bf16_f32 v133, v74, v75
	ds_read_b64_tr_b16 v[72:73], v190 offset:31744
	ds_read_b64_tr_b16 v[74:75], v190 offset:32256
	v_mfma_f32_32x32x16_bf16 v[32:47], v[164:167], v[116:119], v[32:47]
	v_add_f32_e32 v92, v78, v92
	v_add_f32_e32 v92, v79, v92
	v_add_f32_e32 v92, 0, v92
	v_cvt_pk_bf16_f32 v134, v76, v77
	v_cvt_pk_bf16_f32 v135, v78, v79
	v_mfma_f32_32x32x16_bf16 v[48:63], v[148:151], v[96:99], v[48:63]
	s_mov_b64 s[62:63], 0x8190c00
	v_lshl_add_u64 v[76:77], v[214:215], 0, s[62:63]
	s_add_i32 s46, s47, s97
	s_mov_b32 s62, m0
	s_mov_b32 m0, s46
	s_nop 0
	global_load_lds_dwordx4 v[76:77], off
	s_mov_b32 m0, s62
	s_mov_b64 s[62:63], 0x80f1000
	v_lshl_add_u64 v[76:77], v[216:217], 0, s[62:63]
	s_add_i32 s46, s43, s70
	v_mfma_f32_32x32x16_bf16 v[32:47], v[152:155], v[96:99], v[32:47]
	s_mov_b32 s62, m0
	s_mov_b32 m0, s46
	s_nop 0
	global_load_lds_dwordx4 v[76:77], off
	s_mov_b32 m0, s62
	s_nop 4
	v_max_f32_e32 v76, v48, v49
	v_add_f32_e32 v243, v197, v92
	s_nop 2
	v_max3_f32 v77, v50, v51, v33
	v_max3_f32 v76, v76, v32, v34
	v_max3_f32 v76, v76, v35, v52
	v_max3_f32 v77, v77, v54, v55
	v_max3_f32 v76, v76, v53, v36
	v_max3_f32 v77, v77, v38, v39
	v_max3_f32 v76, v76, v37, v56
	v_max3_f32 v77, v77, v58, v59
	v_max3_f32 v76, v76, v57, v40
	v_max3_f32 v77, v77, v42, v43
	v_max3_f32 v76, v76, v41, v60
	v_max3_f32 v77, v77, v62, v63
	v_max3_f32 v76, v76, v61, v44
	v_max3_f32 v77, v77, v46, v47
	v_max3_f32 v76, v76, v45, v77
	v_mov_b32_e32 v77, v76
	s_nop 1
	v_permlane32_swap_b32_e32 v76, v77
	v_max_f32_e32 v76, v76, v77
	v_cmp_lt_f32_e32 vcc, s84, v76
	s_cmp_lg_u64 vcc, 0
	s_cselect_b64 s[62:63], -1, 0
	s_cbranch_vccnz .LBB0_283

.LBB0_280:
	v_max_f32_e32 v45, 0, v44
	v_exp_f32_e64 v44, -v45
	s_and_saveexec_b64 s[64:65], s[6:7]
	ds_write_b32 v236, v44 offset:49152
	s_or_b64 exec, exec, s[64:65]
	v_add_f32_e32 v241, v241, v45
	v_sub_f32_e32 v95, v95, v45
	v_sub_f32_e32 v94, v94, v45
	v_sub_f32_e32 v93, v93, v45
	v_sub_f32_e32 v92, v92, v45
	v_sub_f32_e32 v91, v91, v45
	v_sub_f32_e32 v90, v90, v45
	v_sub_f32_e32 v89, v89, v45
	v_sub_f32_e32 v88, v88, v45
	v_sub_f32_e32 v87, v87, v45
	v_sub_f32_e32 v86, v86, v45
	v_sub_f32_e32 v85, v85, v45
	v_sub_f32_e32 v84, v84, v45
	v_sub_f32_e32 v83, v83, v45
	v_sub_f32_e32 v82, v82, v45
	v_sub_f32_e32 v81, v81, v45
	v_sub_f32_e32 v80, v80, v45
	v_sub_f32_e32 v79, v79, v45
	v_sub_f32_e32 v78, v78, v45
	v_sub_f32_e32 v77, v77, v45
	v_sub_f32_e32 v76, v76, v45
	v_sub_f32_e32 v75, v75, v45
	v_sub_f32_e32 v74, v74, v45
	v_sub_f32_e32 v73, v73, v45
	v_sub_f32_e32 v72, v72, v45
	v_sub_f32_e32 v71, v71, v45
	v_sub_f32_e32 v70, v70, v45
	v_sub_f32_e32 v69, v69, v45
	v_sub_f32_e32 v68, v68, v45
	v_sub_f32_e32 v67, v67, v45
	v_sub_f32_e32 v66, v66, v45
	v_sub_f32_e32 v65, v65, v45
	v_sub_f32_e32 v64, v64, v45
	v_xor_b32_e32 v45, 0x80000000, v241
	v_cvt_pk_bf16_f32 v45, v45, 0
	v_lshlrev_b32_e32 v45, 16, v45
	v_sub_f32_e64 v46, -v241, v45
	v_cvt_pk_bf16_f32 v47, v46, 0
	v_and_b32_e32 v60, 0xffff, v47
	v_lshlrev_b32_e32 v47, 16, v47
	v_sub_f32_e32 v46, v46, v47
	v_cvt_pk_bf16_f32 v46, v46, 0
	v_or_b32_e32 v45, 0x3f80, v45
	v_lshl_or_b32 v46, v46, 16, v60
	v_cndmask_b32_e64 v98, 0, v46, s[6:7]
	v_cndmask_b32_e64 v97, 0, v45, s[6:7]
	v_mul_f32_e32 v197, v197, v44
	s_branch .LBB0_273
.LBB0_283:
	v_max_f32_e32 v77, 0, v76
	v_exp_f32_e64 v76, -v77
	s_and_saveexec_b64 s[64:65], s[6:7]
	ds_write_b32 v236, v76 offset:49152
	s_or_b64 exec, exec, s[64:65]
	v_add_f32_e32 v241, v241, v77
	v_sub_f32_e32 v63, v63, v77
	v_sub_f32_e32 v62, v62, v77
	v_sub_f32_e32 v61, v61, v77
	v_sub_f32_e32 v60, v60, v77
	v_sub_f32_e32 v59, v59, v77
	v_sub_f32_e32 v58, v58, v77
	v_sub_f32_e32 v57, v57, v77
	v_sub_f32_e32 v56, v56, v77
	v_sub_f32_e32 v55, v55, v77
	v_sub_f32_e32 v54, v54, v77
	v_sub_f32_e32 v53, v53, v77
	v_sub_f32_e32 v52, v52, v77
	v_sub_f32_e32 v51, v51, v77
	v_sub_f32_e32 v50, v50, v77
	v_sub_f32_e32 v49, v49, v77
	v_sub_f32_e32 v48, v48, v77
	v_sub_f32_e32 v47, v47, v77
	v_sub_f32_e32 v46, v46, v77
	v_sub_f32_e32 v45, v45, v77
	v_sub_f32_e32 v44, v44, v77
	v_sub_f32_e32 v43, v43, v77
	v_sub_f32_e32 v42, v42, v77
	v_sub_f32_e32 v41, v41, v77
	v_sub_f32_e32 v40, v40, v77
	v_sub_f32_e32 v39, v39, v77
	v_sub_f32_e32 v38, v38, v77
	v_sub_f32_e32 v37, v37, v77
	v_sub_f32_e32 v36, v36, v77
	v_sub_f32_e32 v35, v35, v77
	v_sub_f32_e32 v34, v34, v77
	v_sub_f32_e32 v33, v33, v77
	v_sub_f32_e32 v32, v32, v77
	v_xor_b32_e32 v77, 0x80000000, v241
	v_cvt_pk_bf16_f32 v77, v77, 0
	v_lshlrev_b32_e32 v77, 16, v77
	v_sub_f32_e64 v78, -v241, v77
	v_cvt_pk_bf16_f32 v79, v78, 0
	v_and_b32_e32 v92, 0xffff, v79
	v_lshlrev_b32_e32 v79, 16, v79
	v_sub_f32_e32 v78, v78, v79
	v_cvt_pk_bf16_f32 v78, v78, 0
	v_or_b32_e32 v77, 0x3f80, v77
	v_lshl_or_b32 v78, v78, 16, v92
	v_cndmask_b32_e64 v98, 0, v78, s[6:7]
	v_cndmask_b32_e64 v97, 0, v77, s[6:7]
	v_mul_f32_e32 v243, v243, v76
	s_branch .LBB0_276

.LBB0_290:
	v_add_u32_e32 v196, s46, v240
	ds_read_b64_tr_b16 v[192:193], v196 offset:24576
	ds_read_b64_tr_b16 v[194:195], v196 offset:25088
	v_add_f32_e32 v64, v48, v49
	v_add_f32_e32 v64, v50, v64
	v_add_f32_e32 v64, v51, v64
	v_add_f32_e32 v64, v52, v64
	v_add_f32_e32 v80, v53, v64
	s_waitcnt lgkmcnt(11)
	v_mfma_f32_32x32x16_bf16 v[64:79], v[184:187], v[128:131], 0
	v_cvt_pk_bf16_f32 v144, v48, v49
	v_cvt_pk_bf16_f32 v145, v50, v51
	ds_read_b64_tr_b16 v[188:189], v196 offset:28672
	ds_read_b64_tr_b16 v[190:191], v196 offset:29184
	v_add_f32_e32 v48, v54, v80
	v_add_f32_e32 v48, v55, v48
	v_add_f32_e32 v48, v56, v48
	v_add_f32_e32 v48, v57, v48
	v_cvt_pk_bf16_f32 v146, v52, v53
	v_cvt_pk_bf16_f32 v147, v54, v55
	s_waitcnt lgkmcnt(12)
	v_mfma_f32_32x32x16_bf16 v[80:95], v[176:179], v[128:131], 0
	ds_read_b64_tr_b16 v[184:185], v196 offset:25600
	ds_read_b64_tr_b16 v[186:187], v196 offset:26112
	s_waitcnt lgkmcnt(11)
	v_mfma_f32_32x32x16_bf16 v[64:79], v[180:183], v[124:127], v[64:79]
	v_add_f32_e32 v48, v58, v48
	v_add_f32_e32 v48, v59, v48
	v_add_f32_e32 v48, v60, v48
	v_add_f32_e32 v48, v61, v48
	v_cvt_pk_bf16_f32 v140, v56, v57
	v_cvt_pk_bf16_f32 v141, v58, v59
	ds_read_b64_tr_b16 v[176:177], v196 offset:29696
	ds_read_b64_tr_b16 v[178:179], v196 offset:30208
	v_add_f32_e32 v48, v62, v48
	v_add_f32_e32 v48, v63, v48
	v_add_f32_e32 v48, v32, v48
	v_add_f32_e32 v48, v33, v48
	v_cvt_pk_bf16_f32 v142, v60, v61
	v_cvt_pk_bf16_f32 v143, v62, v63
	s_waitcnt lgkmcnt(12)
	v_mfma_f32_32x32x16_bf16 v[80:95], v[172:175], v[124:127], v[80:95]
	ds_read_b64_tr_b16 v[172:173], v196 offset:26624
	ds_read_b64_tr_b16 v[174:175], v196 offset:27136
	s_waitcnt lgkmcnt(13)
	v_mfma_f32_32x32x16_bf16 v[64:79], v[168:171], v[120:123], v[64:79]
	v_add_f32_e32 v48, v34, v48
	v_add_f32_e32 v48, v35, v48
	v_add_f32_e32 v48, v36, v48
	v_add_f32_e32 v48, v37, v48
	v_cvt_pk_bf16_f32 v136, v32, v33
	v_cvt_pk_bf16_f32 v137, v34, v35
	ds_read_b64_tr_b16 v[128:129], v196 offset:30720
	ds_read_b64_tr_b16 v[130:131], v196 offset:31232
	v_add_f32_e32 v32, v38, v48
	v_add_f32_e32 v32, v39, v32
	v_add_f32_e32 v32, v40, v32
	v_add_f32_e32 v32, v41, v32
	v_cvt_pk_bf16_f32 v138, v36, v37
	v_cvt_pk_bf16_f32 v139, v38, v39
	s_waitcnt lgkmcnt(14)
	v_mfma_f32_32x32x16_bf16 v[80:95], v[164:167], v[120:123], v[80:95]
	ds_read_b64_tr_b16 v[124:125], v196 offset:27648
	ds_read_b64_tr_b16 v[126:127], v196 offset:28160
	s_waitcnt lgkmcnt(14)
; __device__ __forceinline__ void cmask(f32x16& p0, f32x16& p1, int jb, int qrel, int hi) {
;     const float NEG = -INFINITY; int kb = 64 * jb + 4 * hi;
; #pragma unroll
;     for (int r = 0; r < 16; ++r) { int kv = kb + (r & 3) + 8 * (r >> 2); if (kv > qrel) p0[r] = NEG; if (kv + 32 > qrel) p1[r] = NEG; }
; }
	v_mfma_f32_32x32x16_bf16 v[64:79], v[160:163], v[116:119], v[64:79]
	v_add_f32_e32 v32, v42, v32
	v_add_f32_e32 v32, v43, v32
	v_add_f32_e32 v32, v44, v32
	v_add_f32_e32 v32, v45, v32
	v_cvt_pk_bf16_f32 v132, v40, v41
	v_cvt_pk_bf16_f32 v133, v42, v43
	ds_read_b64_tr_b16 v[120:121], v196 offset:31744
	ds_read_b64_tr_b16 v[122:123], v196 offset:32256
	v_add_f32_e32 v32, v46, v32
	v_add_f32_e32 v32, v47, v32
	v_add_f32_e32 v160, 0, v32
	v_cvt_pk_bf16_f32 v134, v44, v45
	v_cvt_pk_bf16_f32 v135, v46, v47
	v_mfma_f32_32x32x16_bf16 v[80:95], v[156:159], v[116:119], v[80:95]
	v_mfma_f32_32x32x16_bf16 v[80:95], v[148:151], v[96:99], v[80:95]
	v_or_b32_e32 v32, 0xe0, v205
	v_or_b32_e32 v33, 0xc0, v205
	v_cmp_le_i32_e32 vcc, v32, v237
	v_or_b32_e32 v34, 0xc2, v205
	v_or_b32_e32 v35, 0xc3, v205
	v_or_b32_e32 v36, 0xc8, v205
	v_or_b32_e32 v37, 0xc9, v205
	v_mfma_f32_32x32x16_bf16 v[64:79], v[152:155], v[96:99], v[64:79]
	s_nop 3
	v_cndmask_b32_e32 v32, v228, v80, vcc
	v_cmp_lt_i32_e32 vcc, v33, v237
	v_or_b32_e32 v38, 0xca, v205
	v_or_b32_e32 v39, 0xcb, v205
	v_or_b32_e32 v40, 0xd0, v205
	v_or_b32_e32 v41, 0xd1, v205
	v_or_b32_e32 v42, 0xd2, v205
	s_nop 0
	v_cndmask_b32_e32 v49, v228, v65, vcc
	v_cmp_le_i32_e32 vcc, v33, v237
	v_or_b32_e32 v33, 0xe1, v205
	v_or_b32_e32 v43, 0xd3, v205
	v_cndmask_b32_e32 v48, v228, v64, vcc
	v_cmp_le_i32_e32 vcc, v33, v237
	v_or_b32_e32 v44, 0xd8, v205
	v_or_b32_e32 v45, 0xd9, v205
	v_cndmask_b32_e32 v33, v228, v81, vcc
	v_cmp_le_i32_e32 vcc, v34, v237
	v_or_b32_e32 v34, 0xe2, v205
	v_max_f32_e32 v64, v49, v49
	v_cndmask_b32_e32 v50, v228, v66, vcc
	v_cmp_le_i32_e32 vcc, v34, v237
	v_max_f32_e32 v65, v48, v48
	v_max_f32_e32 v64, v65, v64
	v_cndmask_b32_e32 v34, v228, v82, vcc
	v_cmp_le_i32_e32 vcc, v35, v237
	v_or_b32_e32 v35, 0xe3, v205
	v_or_b32_e32 v46, 0xda, v205
	v_cndmask_b32_e32 v51, v228, v67, vcc
	v_cmp_le_i32_e32 vcc, v35, v237
	v_max3_f32 v65, v50, v51, v33
	v_max3_f32 v64, v64, v32, v34
	v_cndmask_b32_e32 v35, v228, v83, vcc
	v_cmp_le_i32_e32 vcc, v36, v237
	v_or_b32_e32 v36, 0xe8, v205
	v_or_b32_e32 v47, 0xdb, v205
	v_cndmask_b32_e32 v52, v228, v68, vcc
	v_cmp_le_i32_e32 vcc, v36, v237
	v_max3_f32 v64, v64, v35, v52
	s_nop 0
	v_cndmask_b32_e32 v36, v228, v84, vcc
	v_cmp_le_i32_e32 vcc, v37, v237
	v_or_b32_e32 v37, 0xe9, v205
	s_nop 0
	v_cndmask_b32_e32 v53, v228, v69, vcc
	v_cmp_le_i32_e32 vcc, v37, v237
	v_max3_f32 v64, v64, v53, v36
	s_nop 0
	v_cndmask_b32_e32 v37, v228, v85, vcc
	v_cmp_le_i32_e32 vcc, v38, v237
	v_or_b32_e32 v38, 0xea, v205
	s_nop 0
	v_cndmask_b32_e32 v54, v228, v70, vcc
	v_cmp_le_i32_e32 vcc, v38, v237
	s_nop 1
	v_cndmask_b32_e32 v38, v228, v86, vcc
	v_cmp_le_i32_e32 vcc, v39, v237
	v_or_b32_e32 v39, 0xeb, v205
	s_nop 0
	v_cndmask_b32_e32 v55, v228, v71, vcc
	v_cmp_le_i32_e32 vcc, v39, v237
	v_max3_f32 v65, v65, v54, v55
	s_nop 0
	v_cndmask_b32_e32 v39, v228, v87, vcc
	v_cmp_le_i32_e32 vcc, v40, v237
	v_or_b32_e32 v40, 0xf0, v205
	v_max3_f32 v65, v65, v38, v39
	v_cndmask_b32_e32 v56, v228, v72, vcc
	v_cmp_le_i32_e32 vcc, v40, v237
	v_max3_f32 v64, v64, v37, v56
	s_nop 0
	v_cndmask_b32_e32 v40, v228, v88, vcc
	v_cmp_le_i32_e32 vcc, v41, v237
	v_or_b32_e32 v41, 0xf1, v205
	s_nop 0
	v_cndmask_b32_e32 v57, v228, v73, vcc
	v_cmp_le_i32_e32 vcc, v41, v237
	v_max3_f32 v64, v64, v57, v40
	s_nop 0
	v_cndmask_b32_e32 v41, v228, v89, vcc
	v_cmp_le_i32_e32 vcc, v42, v237
	v_or_b32_e32 v42, 0xf2, v205
	s_nop 0
	v_cndmask_b32_e32 v58, v228, v74, vcc
	v_cmp_le_i32_e32 vcc, v42, v237
	s_nop 1
	v_cndmask_b32_e32 v42, v228, v90, vcc
	v_cmp_le_i32_e32 vcc, v43, v237
	v_or_b32_e32 v43, 0xf3, v205
	s_nop 0
	v_cndmask_b32_e32 v59, v228, v75, vcc
	v_cmp_le_i32_e32 vcc, v43, v237
	v_max3_f32 v65, v65, v58, v59
	s_nop 0
	v_cndmask_b32_e32 v43, v228, v91, vcc
	v_cmp_le_i32_e32 vcc, v44, v237
	v_or_b32_e32 v44, 0xf8, v205
	v_max3_f32 v65, v65, v42, v43
	v_cndmask_b32_e32 v60, v228, v76, vcc
	v_cmp_le_i32_e32 vcc, v44, v237
	v_max3_f32 v64, v64, v41, v60
	s_nop 0
	v_cndmask_b32_e32 v44, v228, v92, vcc
	v_cmp_le_i32_e32 vcc, v45, v237
	v_or_b32_e32 v45, 0xf9, v205
	s_nop 0
	v_cndmask_b32_e32 v61, v228, v77, vcc
	v_cmp_le_i32_e32 vcc, v45, v237
	v_max3_f32 v66, v64, v61, v44
	v_add_f32_e32 v64, v243, v160
	v_cndmask_b32_e32 v45, v228, v93, vcc
	v_cmp_le_i32_e32 vcc, v46, v237
	v_or_b32_e32 v46, 0xfa, v205
	s_nop 0
	v_cndmask_b32_e32 v62, v228, v78, vcc
	v_cmp_le_i32_e32 vcc, v46, v237
	s_nop 1
	v_cndmask_b32_e32 v46, v228, v94, vcc
	v_cmp_le_i32_e32 vcc, v47, v237
	v_or_b32_e32 v47, 0xfb, v205
	s_nop 0
	v_cndmask_b32_e32 v63, v228, v79, vcc
	v_cmp_le_i32_e32 vcc, v47, v237
	v_max3_f32 v65, v65, v62, v63
	s_nop 0
	v_cndmask_b32_e32 v47, v228, v95, vcc
	v_max3_f32 v65, v65, v46, v47
	v_max3_f32 v65, v66, v45, v65
	v_mov_b32_e32 v66, v65
	s_nop 1
	v_permlane32_swap_b32_e32 v65, v66
	v_max_f32_e32 v65, v65, v66
	v_cmp_lt_f32_e32 vcc, s84, v65
	s_cmp_lg_u64 vcc, 0
	s_cselect_b64 s[60:61], -1, 0
	s_cbranch_vccnz .LBB0_349

.LBB0_303:
	v_max_f32_e32 v44, v80, v81
	v_max3_f32 v45, v82, v83, v65
	v_max3_f32 v44, v44, v64, v66
	v_max3_f32 v44, v44, v67, v84
	v_max3_f32 v45, v45, v86, v87
	v_max3_f32 v44, v44, v85, v68
	v_max3_f32 v45, v45, v70, v71
	v_max3_f32 v44, v44, v69, v88
	v_max3_f32 v45, v45, v90, v91
	v_max3_f32 v44, v44, v89, v72
	v_max3_f32 v45, v45, v74, v75
	v_max3_f32 v44, v44, v73, v92
	v_max3_f32 v45, v45, v94, v95
	v_max3_f32 v44, v44, v93, v76
	v_max3_f32 v45, v45, v78, v79
	v_max3_f32 v44, v44, v77, v45
	v_mov_b32_e32 v45, v44
	s_nop 1
	v_permlane32_swap_b32_e32 v44, v45
	v_max_f32_e32 v44, v44, v45
	v_cmp_lt_f32_e32 vcc, s84, v44
	s_cmp_lg_u64 vcc, 0
	v_add_f32_e32 v243, v243, v60
	s_cselect_b64 s[8:9], -1, 0
	s_cbranch_vccnz .LBB0_341

.LBB0_314:
	v_add_f32_e32 v243, v243, v72
	v_max_f32_e32 v72, v48, v49
	v_max3_f32 v73, v50, v51, v33
	v_max3_f32 v72, v72, v32, v34
	v_max3_f32 v72, v72, v35, v52
	v_max3_f32 v73, v73, v54, v55
	v_max3_f32 v72, v72, v53, v36
	v_max3_f32 v73, v73, v38, v39
	v_max3_f32 v72, v72, v37, v56
	v_max3_f32 v73, v73, v58, v59
	v_max3_f32 v72, v72, v57, v40
	v_max3_f32 v73, v73, v42, v43
	v_max3_f32 v72, v72, v41, v60
	v_max3_f32 v73, v73, v62, v63
	v_max3_f32 v72, v72, v61, v44
	v_max3_f32 v73, v73, v46, v47
	v_max3_f32 v72, v72, v45, v73
	v_mov_b32_e32 v73, v72
	s_nop 1
	v_permlane32_swap_b32_e32 v72, v73
	v_max_f32_e32 v72, v72, v73
	v_cmp_lt_f32_e32 vcc, s84, v72
	s_cmp_lg_u64 vcc, 0
	s_cselect_b64 s[64:65], -1, 0
	s_cbranch_vccnz .LBB0_344

.LBB0_341:
	v_max_f32_e32 v45, 0, v44
	v_exp_f32_e64 v44, -v45
	s_and_saveexec_b64 s[62:63], s[6:7]
	ds_write_b32 v236, v44 offset:49152
	s_or_b64 exec, exec, s[62:63]
	v_add_f32_e32 v241, v241, v45
	v_sub_f32_e32 v95, v95, v45
	v_sub_f32_e32 v94, v94, v45
	v_sub_f32_e32 v93, v93, v45
	v_sub_f32_e32 v92, v92, v45
	v_sub_f32_e32 v91, v91, v45
	v_sub_f32_e32 v90, v90, v45
	v_sub_f32_e32 v89, v89, v45
	v_sub_f32_e32 v88, v88, v45
	v_sub_f32_e32 v87, v87, v45
	v_sub_f32_e32 v86, v86, v45
	v_sub_f32_e32 v85, v85, v45
	v_sub_f32_e32 v84, v84, v45
	v_sub_f32_e32 v83, v83, v45
	v_sub_f32_e32 v82, v82, v45
	v_sub_f32_e32 v81, v81, v45
	v_sub_f32_e32 v80, v80, v45
	v_sub_f32_e32 v79, v79, v45
	v_sub_f32_e32 v78, v78, v45
	v_sub_f32_e32 v77, v77, v45
	v_sub_f32_e32 v76, v76, v45
	v_sub_f32_e32 v75, v75, v45
	v_sub_f32_e32 v74, v74, v45
	v_sub_f32_e32 v73, v73, v45
	v_sub_f32_e32 v72, v72, v45
	v_sub_f32_e32 v71, v71, v45
	v_sub_f32_e32 v70, v70, v45
	v_sub_f32_e32 v69, v69, v45
	v_sub_f32_e32 v68, v68, v45
	v_sub_f32_e32 v67, v67, v45
	v_sub_f32_e32 v66, v66, v45
	v_sub_f32_e32 v65, v65, v45
	v_sub_f32_e32 v64, v64, v45
	v_xor_b32_e32 v45, 0x80000000, v241
	v_cvt_pk_bf16_f32 v45, v45, 0
	v_lshlrev_b32_e32 v45, 16, v45
	v_sub_f32_e64 v46, -v241, v45
	v_cvt_pk_bf16_f32 v47, v46, 0
	v_and_b32_e32 v60, 0xffff, v47
	v_lshlrev_b32_e32 v47, 16, v47
	v_sub_f32_e32 v46, v46, v47
	v_cvt_pk_bf16_f32 v46, v46, 0
	v_or_b32_e32 v45, 0x3f80, v45
	v_lshl_or_b32 v46, v46, 16, v60
	v_cndmask_b32_e64 v98, 0, v46, s[6:7]
	v_cndmask_b32_e64 v97, 0, v45, s[6:7]
	v_mul_f32_e32 v243, v243, v44
	s_branch .LBB0_304
.LBB0_344:
	v_max_f32_e32 v73, 0, v72
	v_exp_f32_e64 v72, -v73
	s_and_saveexec_b64 s[8:9], s[6:7]
	ds_write_b32 v236, v72 offset:49152
	s_or_b64 exec, exec, s[8:9]
	v_add_f32_e32 v241, v241, v73
	v_sub_f32_e32 v63, v63, v73
	v_sub_f32_e32 v62, v62, v73
	v_sub_f32_e32 v61, v61, v73
	v_sub_f32_e32 v60, v60, v73
	v_sub_f32_e32 v59, v59, v73
	v_sub_f32_e32 v58, v58, v73
	v_sub_f32_e32 v57, v57, v73
	v_sub_f32_e32 v56, v56, v73
	v_sub_f32_e32 v55, v55, v73
	v_sub_f32_e32 v54, v54, v73
	v_sub_f32_e32 v53, v53, v73
	v_sub_f32_e32 v52, v52, v73
	v_sub_f32_e32 v51, v51, v73
	v_sub_f32_e32 v50, v50, v73
	v_sub_f32_e32 v49, v49, v73
	v_sub_f32_e32 v48, v48, v73
	v_sub_f32_e32 v47, v47, v73
	v_sub_f32_e32 v46, v46, v73
	v_sub_f32_e32 v45, v45, v73
	v_sub_f32_e32 v44, v44, v73
	v_sub_f32_e32 v43, v43, v73
	v_sub_f32_e32 v42, v42, v73
	v_sub_f32_e32 v41, v41, v73
	v_sub_f32_e32 v40, v40, v73
	v_sub_f32_e32 v39, v39, v73
	v_sub_f32_e32 v38, v38, v73
	v_sub_f32_e32 v37, v37, v73
	v_sub_f32_e32 v36, v36, v73
	v_sub_f32_e32 v35, v35, v73
	v_sub_f32_e32 v34, v34, v73
	v_sub_f32_e32 v33, v33, v73
	v_sub_f32_e32 v32, v32, v73
	v_xor_b32_e32 v73, 0x80000000, v241
	v_cvt_pk_bf16_f32 v73, v73, 0
	v_lshlrev_b32_e32 v73, 16, v73
	v_sub_f32_e64 v74, -v241, v73
	v_cvt_pk_bf16_f32 v75, v74, 0
	v_and_b32_e32 v76, 0xffff, v75
	v_lshlrev_b32_e32 v75, 16, v75
	v_sub_f32_e32 v74, v74, v75
	v_cvt_pk_bf16_f32 v74, v74, 0
	v_or_b32_e32 v73, 0x3f80, v73
	v_lshl_or_b32 v74, v74, 16, v76
	v_cndmask_b32_e64 v98, 0, v74, s[6:7]
	v_cndmask_b32_e64 v97, 0, v73, s[6:7]
	v_mul_f32_e32 v243, v243, v72
	s_branch .LBB0_315

.LBB0_349:
	v_max_f32_e32 v66, 0, v65
	v_exp_f32_e64 v65, -v66
	s_and_saveexec_b64 s[62:63], s[6:7]
	ds_write_b32 v236, v65 offset:49152
	s_or_b64 exec, exec, s[62:63]
	v_sub_f32_e32 v63, v63, v66
	v_sub_f32_e32 v62, v62, v66
	v_sub_f32_e32 v61, v61, v66
	v_sub_f32_e32 v60, v60, v66
	v_sub_f32_e32 v59, v59, v66
	v_sub_f32_e32 v58, v58, v66
	v_sub_f32_e32 v57, v57, v66
	v_sub_f32_e32 v56, v56, v66
	v_sub_f32_e32 v55, v55, v66
	v_sub_f32_e32 v54, v54, v66
	v_sub_f32_e32 v53, v53, v66
	v_sub_f32_e32 v52, v52, v66
	v_sub_f32_e32 v51, v51, v66
	v_sub_f32_e32 v50, v50, v66
	v_sub_f32_e32 v49, v49, v66
	v_sub_f32_e32 v48, v48, v66
	v_sub_f32_e32 v47, v47, v66
	v_sub_f32_e32 v46, v46, v66
	v_sub_f32_e32 v45, v45, v66
	v_sub_f32_e32 v44, v44, v66
	v_sub_f32_e32 v43, v43, v66
	v_sub_f32_e32 v42, v42, v66
	v_sub_f32_e32 v41, v41, v66
	v_sub_f32_e32 v40, v40, v66
	v_sub_f32_e32 v39, v39, v66
	v_sub_f32_e32 v38, v38, v66
	v_sub_f32_e32 v37, v37, v66
	v_sub_f32_e32 v36, v36, v66
	v_sub_f32_e32 v35, v35, v66
	v_sub_f32_e32 v34, v34, v66
	v_sub_f32_e32 v33, v33, v66
	v_sub_f32_e32 v32, v32, v66
	v_mul_f32_e32 v64, v64, v65
	s_branch .LBB0_291

;     __device__ __forceinline__ void operator()(Acc& acc, const Unit& u, int wr, int wc, int fr, int fq, PG8_LAS unsigned char* xl) const {
;     ...
;             for (int m = 0; m < 4; ++m) { const int rl = ai * HALF + wr * 64 + m * 16 + fr; const float rs = S[rl];
;                 float mx = -INFINITY;
; #pragma unroll
;                 for (int bj = 0; bj < 2; ++bj)
; #pragma unroll
;                     for (int n = 0; n < 2; ++n) { const f32x4 v = acc[ai][bj][m][n] * rs; acc[ai][bj][m][n] = v; mx = fmaxf(mx, fmaxf(fmaxf(v[0], v[1]), fmaxf(v[2], v[3]))); }
;                 mx = fmaxf(mx, __shfl_xor(mx, 16)); mx = fmaxf(mx, __shfl_xor(mx, 32));
;                 float s = 0.f;
; #pragma unroll
;                 for (int bj = 0; bj < 2; ++bj)
; #pragma unroll
;                     for (int n = 0; n < 2; ++n) { f32x4 v = acc[ai][bj][m][n];
; #pragma unroll
;                         for (int e = 0; e < 4; ++e) { v[e] = __builtin_amdgcn_exp2f(v[e] - mx); s += v[e]; }
;                         acc[ai][bj][m][n] = v; }
;                 s += __shfl_xor(s, 16); s += __shfl_xor(s, 32);
;                 if (fq == 0) X[rl * 4 + wc] = (f32x2){mx, s};
.LBB0_582:
	s_or_b64 exec, exec, s[50:51]
	s_waitcnt vmcnt(0) lgkmcnt(0)
	s_barrier
	ds_read_b32 v146, v157
	v_and_b32_e32 v148, 64, v186
	v_xor_b32_e32 v147, 16, v186
	v_add_u32_e32 v150, 64, v148
	v_cmp_lt_i32_e32 vcc, v147, v150
	s_nop 1
	v_cndmask_b32_e32 v147, v186, v147, vcc
	s_waitcnt lgkmcnt(0)
	v_pk_mul_f32 v[126:127], v[126:127], v[146:147] op_sel_hi:[1,0]
	v_lshlrev_b32_e32 v187, 2, v147
	v_pk_mul_f32 v[124:125], v[124:125], v[146:147] op_sel_hi:[1,0]
	v_max_f32_e32 v147, v126, v127
	v_max3_f32 v147, v124, v125, v147
	v_pk_mul_f32 v[122:123], v[122:123], v[146:147] op_sel_hi:[1,0]
	v_pk_mul_f32 v[148:149], v[120:121], v[146:147] op_sel_hi:[1,0]
	v_max_f32_e32 v120, v122, v123
	v_max3_f32 v120, v148, v149, v120
	v_pk_mul_f32 v[118:119], v[118:119], v[146:147] op_sel_hi:[1,0]
	v_pk_mul_f32 v[114:115], v[114:115], v[146:147] op_sel_hi:[1,0]
	v_max3_f32 v120, v147, s75, v120
	v_pk_mul_f32 v[116:117], v[116:117], v[146:147] op_sel_hi:[1,0]
	v_max_f32_e32 v121, v118, v119
	v_pk_mul_f32 v[146:147], v[112:113], v[146:147] op_sel_hi:[1,0]
	v_max_f32_e32 v112, v114, v115
	v_max3_f32 v121, v116, v117, v121
	v_max3_f32 v112, v146, v147, v112
	v_max3_f32 v112, v120, v121, v112
	v_mov_b32_e32 v113, v112
	s_nop 1
	v_permlane16_swap_b32_e32 v112, v113
	v_xor_b32_e32 v120, 32, v186
	v_cmp_lt_i32_e32 vcc, v120, v150
	s_waitcnt lgkmcnt(0)
	v_cndmask_b32_e32 v120, v186, v120, vcc
	v_lshlrev_b32_e32 v188, 2, v120
	v_max_f32_e32 v112, v112, v113
	v_mov_b32_e32 v113, v112
	s_nop 1
	v_permlane32_swap_b32_e32 v112, v113
	s_waitcnt lgkmcnt(0)
	v_max_f32_e32 v112, v112, v113
	v_sub_f32_e32 v113, v124, v112
	v_exp_f32_e32 v120, v113
	v_sub_f32_e32 v113, v125, v112
	v_exp_f32_e32 v121, v113
	v_sub_f32_e32 v113, v126, v112
	v_exp_f32_e32 v126, v113
	v_sub_f32_e32 v113, v127, v112
	v_exp_f32_e32 v127, v113
	v_sub_f32_e32 v124, v148, v112
	v_add_f32_e32 v113, 0, v120
	v_exp_f32_e32 v124, v124
	v_sub_f32_e32 v125, v149, v112
	v_add_f32_e32 v113, v121, v113
	v_exp_f32_e32 v125, v125
	v_sub_f32_e32 v122, v122, v112
	v_add_f32_e32 v113, v126, v113
	v_exp_f32_e32 v150, v122
	v_sub_f32_e32 v122, v123, v112
	v_add_f32_e32 v113, v127, v113
	v_exp_f32_e32 v151, v122
	v_sub_f32_e32 v116, v116, v112
	v_add_f32_e32 v113, v124, v113
	v_exp_f32_e32 v122, v116
	v_sub_f32_e32 v116, v117, v112
	v_add_f32_e32 v113, v125, v113
	v_exp_f32_e32 v123, v116
	v_sub_f32_e32 v116, v118, v112
	v_add_f32_e32 v113, v150, v113
	v_exp_f32_e32 v148, v116
	v_sub_f32_e32 v116, v119, v112
	v_add_f32_e32 v113, v151, v113
	v_exp_f32_e32 v149, v116
	v_sub_f32_e32 v116, v146, v112
	v_add_f32_e32 v113, v122, v113
	v_exp_f32_e32 v146, v116
	v_sub_f32_e32 v116, v147, v112
	v_add_f32_e32 v113, v123, v113
	v_exp_f32_e32 v147, v116
	v_sub_f32_e32 v114, v114, v112
	v_add_f32_e32 v113, v148, v113
	v_exp_f32_e32 v152, v114
	v_sub_f32_e32 v114, v115, v112
	v_add_f32_e32 v113, v149, v113
	v_exp_f32_e32 v153, v114
	v_add_f32_e32 v113, v146, v113
	v_add_f32_e32 v113, v147, v113
	v_add_f32_e32 v113, v152, v113
	v_add_f32_e32 v113, v153, v113
	v_mov_b32_e32 v114, v113
	s_nop 1
	v_permlane16_swap_b32_e32 v113, v114
	s_waitcnt lgkmcnt(0)
	v_add_f32_e32 v113, v113, v114
	v_mov_b32_e32 v114, v113
	s_nop 1
	v_permlane32_swap_b32_e32 v113, v114
	s_and_saveexec_b64 s[2:3], s[6:7]
	s_cbranch_execz .LBB0_584
	s_waitcnt lgkmcnt(0)
	v_add_f32_e32 v113, v113, v114
	v_add_u32_e32 v114, s67, v158
	ds_write_b64 v114, v[112:113]
.LBB0_584:
	s_or_b64 exec, exec, s[2:3]
	ds_read_b32 v112, v160
	s_waitcnt lgkmcnt(0)
	v_pk_mul_f32 v[110:111], v[110:111], v[112:113] op_sel_hi:[1,0]
	v_pk_mul_f32 v[106:107], v[106:107], v[112:113] op_sel_hi:[1,0]
	v_pk_mul_f32 v[108:109], v[108:109], v[112:113] op_sel_hi:[1,0]
	v_pk_mul_f32 v[114:115], v[104:105], v[112:113] op_sel_hi:[1,0]
	v_max_f32_e32 v104, v110, v111
	v_max_f32_e32 v105, v106, v107
	v_max3_f32 v104, v108, v109, v104
	v_max3_f32 v105, v114, v115, v105
	v_pk_mul_f32 v[102:103], v[102:103], v[112:113] op_sel_hi:[1,0]
	v_pk_mul_f32 v[98:99], v[98:99], v[112:113] op_sel_hi:[1,0]
	v_max3_f32 v104, v104, s75, v105
	v_pk_mul_f32 v[100:101], v[100:101], v[112:113] op_sel_hi:[1,0]
	v_max_f32_e32 v105, v102, v103
	v_pk_mul_f32 v[112:113], v[96:97], v[112:113] op_sel_hi:[1,0]
	v_max_f32_e32 v96, v98, v99
	v_max3_f32 v105, v100, v101, v105
	v_max3_f32 v96, v112, v113, v96
	v_max3_f32 v96, v104, v105, v96
	v_mov_b32_e32 v97, v96
	s_nop 1
	v_permlane16_swap_b32_e32 v96, v97
	s_waitcnt lgkmcnt(0)
	v_max_f32_e32 v96, v96, v97
	v_mov_b32_e32 v97, v96
	s_nop 1
	v_permlane32_swap_b32_e32 v96, v97
	s_waitcnt lgkmcnt(0)
	v_max_f32_e32 v96, v96, v97
	v_sub_f32_e32 v97, v108, v96
	v_exp_f32_e32 v104, v97
	v_sub_f32_e32 v97, v109, v96
	v_exp_f32_e32 v105, v97
	v_sub_f32_e32 v97, v110, v96
	v_exp_f32_e32 v110, v97
	v_sub_f32_e32 v97, v111, v96
	v_exp_f32_e32 v111, v97
	v_sub_f32_e32 v108, v114, v96
	v_add_f32_e32 v97, 0, v104
	v_exp_f32_e32 v108, v108
	v_sub_f32_e32 v109, v115, v96
	v_add_f32_e32 v97, v105, v97
	v_exp_f32_e32 v109, v109
	v_sub_f32_e32 v106, v106, v96
	v_add_f32_e32 v97, v110, v97
	v_exp_f32_e32 v116, v106
	v_sub_f32_e32 v106, v107, v96
	v_add_f32_e32 v97, v111, v97
	v_exp_f32_e32 v117, v106
	v_sub_f32_e32 v100, v100, v96
	v_add_f32_e32 v97, v108, v97
	v_exp_f32_e32 v106, v100
	v_sub_f32_e32 v100, v101, v96
	v_add_f32_e32 v97, v109, v97
	v_exp_f32_e32 v107, v100
	v_sub_f32_e32 v100, v102, v96
	v_add_f32_e32 v97, v116, v97
	v_exp_f32_e32 v114, v100
	v_sub_f32_e32 v100, v103, v96
	v_add_f32_e32 v97, v117, v97
	v_exp_f32_e32 v115, v100
	v_sub_f32_e32 v100, v112, v96
	v_add_f32_e32 v97, v106, v97
	v_exp_f32_e32 v112, v100
	v_sub_f32_e32 v100, v113, v96
	v_add_f32_e32 v97, v107, v97
	v_exp_f32_e32 v113, v100
	v_sub_f32_e32 v98, v98, v96
	v_add_f32_e32 v97, v114, v97
	v_exp_f32_e32 v118, v98
	v_sub_f32_e32 v98, v99, v96
	v_add_f32_e32 v97, v115, v97
	v_exp_f32_e32 v119, v98
	v_add_f32_e32 v97, v112, v97
	v_add_f32_e32 v97, v113, v97
	v_add_f32_e32 v97, v118, v97
	v_add_f32_e32 v97, v119, v97
	v_mov_b32_e32 v98, v97
	s_nop 1
	v_permlane16_swap_b32_e32 v97, v98
	s_waitcnt lgkmcnt(0)
	v_add_f32_e32 v97, v97, v98
	v_mov_b32_e32 v98, v97
	s_nop 1
	v_permlane32_swap_b32_e32 v97, v98
	s_and_saveexec_b64 s[2:3], s[6:7]
	s_cbranch_execz .LBB0_586
	s_waitcnt lgkmcnt(0)
	v_add_f32_e32 v97, v97, v98
	v_add_u32_e32 v98, s67, v161
	ds_write_b64 v98, v[96:97]
;     __device__ __forceinline__ void operator()(Acc& acc, const Unit& u, int wr, int wc, int fr, int fq, PG8_LAS unsigned char* xl) const {
;     ...
;             for (int m = 0; m < 4; ++m) { const int rl = ai * HALF + wr * 64 + m * 16 + fr; const float rs = S[rl];
;                 float mx = -INFINITY;
; #pragma unroll
;                 for (int bj = 0; bj < 2; ++bj)
; #pragma unroll
;                     for (int n = 0; n < 2; ++n) { const f32x4 v = acc[ai][bj][m][n] * rs; acc[ai][bj][m][n] = v; mx = fmaxf(mx, fmaxf(fmaxf(v[0], v[1]), fmaxf(v[2], v[3]))); }
;                 mx = fmaxf(mx, __shfl_xor(mx, 16)); mx = fmaxf(mx, __shfl_xor(mx, 32));
;                 float s = 0.f;
; #pragma unroll
;                 for (int bj = 0; bj < 2; ++bj)
; #pragma unroll
;                     for (int n = 0; n < 2; ++n) { f32x4 v = acc[ai][bj][m][n];
; #pragma unroll
;                         for (int e = 0; e < 4; ++e) { v[e] = __builtin_amdgcn_exp2f(v[e] - mx); s += v[e]; }
;                         acc[ai][bj][m][n] = v; }
;                 s += __shfl_xor(s, 16); s += __shfl_xor(s, 32);
;                 if (fq == 0) X[rl * 4 + wc] = (f32x2){mx, s};
.LBB0_586:
	s_or_b64 exec, exec, s[2:3]
	ds_read_b32 v96, v163
	s_waitcnt lgkmcnt(0)
	v_pk_mul_f32 v[94:95], v[94:95], v[96:97] op_sel_hi:[1,0]
	v_pk_mul_f32 v[90:91], v[90:91], v[96:97] op_sel_hi:[1,0]
	v_pk_mul_f32 v[92:93], v[92:93], v[96:97] op_sel_hi:[1,0]
	v_pk_mul_f32 v[98:99], v[88:89], v[96:97] op_sel_hi:[1,0]
	v_max_f32_e32 v88, v94, v95
	v_max_f32_e32 v89, v90, v91
	v_max3_f32 v88, v92, v93, v88
	v_max3_f32 v89, v98, v99, v89
	v_pk_mul_f32 v[86:87], v[86:87], v[96:97] op_sel_hi:[1,0]
	v_pk_mul_f32 v[82:83], v[82:83], v[96:97] op_sel_hi:[1,0]
	v_max3_f32 v88, v88, s75, v89
	v_pk_mul_f32 v[84:85], v[84:85], v[96:97] op_sel_hi:[1,0]
	v_max_f32_e32 v89, v86, v87
	v_pk_mul_f32 v[96:97], v[80:81], v[96:97] op_sel_hi:[1,0]
	v_max_f32_e32 v80, v82, v83
	v_max3_f32 v89, v84, v85, v89
	v_max3_f32 v80, v96, v97, v80
	v_max3_f32 v80, v88, v89, v80
	v_mov_b32_e32 v81, v80
	s_nop 1
	v_permlane16_swap_b32_e32 v80, v81
	s_waitcnt lgkmcnt(0)
	v_max_f32_e32 v80, v80, v81
	v_mov_b32_e32 v81, v80
	s_nop 1
	v_permlane32_swap_b32_e32 v80, v81
	s_waitcnt lgkmcnt(0)
	v_max_f32_e32 v80, v80, v81
	v_sub_f32_e32 v81, v92, v80
	v_exp_f32_e32 v88, v81
	v_sub_f32_e32 v81, v93, v80
	v_exp_f32_e32 v89, v81
	v_sub_f32_e32 v81, v94, v80
	v_exp_f32_e32 v94, v81
	v_sub_f32_e32 v81, v95, v80
	v_exp_f32_e32 v95, v81
	v_sub_f32_e32 v92, v98, v80
	v_add_f32_e32 v81, 0, v88
	v_exp_f32_e32 v92, v92
	v_sub_f32_e32 v93, v99, v80
	v_add_f32_e32 v81, v89, v81
	v_exp_f32_e32 v93, v93
	v_sub_f32_e32 v90, v90, v80
	v_add_f32_e32 v81, v94, v81
	v_exp_f32_e32 v100, v90
	v_sub_f32_e32 v90, v91, v80
	v_add_f32_e32 v81, v95, v81
	v_exp_f32_e32 v101, v90
	v_sub_f32_e32 v84, v84, v80
	v_add_f32_e32 v81, v92, v81
	v_exp_f32_e32 v90, v84
	v_sub_f32_e32 v84, v85, v80
	v_add_f32_e32 v81, v93, v81
	v_exp_f32_e32 v91, v84
	v_sub_f32_e32 v84, v86, v80
	v_add_f32_e32 v81, v100, v81
	v_exp_f32_e32 v98, v84
	v_sub_f32_e32 v84, v87, v80
	v_add_f32_e32 v81, v101, v81
	v_exp_f32_e32 v99, v84
	v_sub_f32_e32 v84, v96, v80
	v_add_f32_e32 v81, v90, v81
	v_exp_f32_e32 v96, v84
	v_sub_f32_e32 v84, v97, v80
	v_add_f32_e32 v81, v91, v81
	v_exp_f32_e32 v97, v84
	v_sub_f32_e32 v82, v82, v80
	v_add_f32_e32 v81, v98, v81
	v_exp_f32_e32 v102, v82
	v_sub_f32_e32 v82, v83, v80
	v_add_f32_e32 v81, v99, v81
	v_exp_f32_e32 v103, v82
	v_add_f32_e32 v81, v96, v81
	v_add_f32_e32 v81, v97, v81
	v_add_f32_e32 v81, v102, v81
	v_add_f32_e32 v81, v103, v81
	v_mov_b32_e32 v82, v81
	s_nop 1
	v_permlane16_swap_b32_e32 v81, v82
	s_waitcnt lgkmcnt(0)
	v_add_f32_e32 v81, v81, v82
	v_mov_b32_e32 v82, v81
	s_nop 1
	v_permlane32_swap_b32_e32 v81, v82
	s_and_saveexec_b64 s[2:3], s[6:7]
	s_cbranch_execz .LBB0_588
	s_waitcnt lgkmcnt(0)
	v_add_f32_e32 v81, v81, v82
	v_add_u32_e32 v82, s67, v164
	ds_write_b64 v82, v[80:81]
.LBB0_588:
	s_or_b64 exec, exec, s[2:3]
	ds_read_b32 v80, v166
	s_waitcnt lgkmcnt(0)
	v_pk_mul_f32 v[78:79], v[78:79], v[80:81] op_sel_hi:[1,0]
	v_pk_mul_f32 v[74:75], v[74:75], v[80:81] op_sel_hi:[1,0]
	v_pk_mul_f32 v[76:77], v[76:77], v[80:81] op_sel_hi:[1,0]
	v_pk_mul_f32 v[82:83], v[72:73], v[80:81] op_sel_hi:[1,0]
	v_max_f32_e32 v72, v78, v79
	v_max_f32_e32 v73, v74, v75
	v_max3_f32 v72, v76, v77, v72
	v_max3_f32 v73, v82, v83, v73
	v_pk_mul_f32 v[70:71], v[70:71], v[80:81] op_sel_hi:[1,0]
	v_pk_mul_f32 v[66:67], v[66:67], v[80:81] op_sel_hi:[1,0]
	v_max3_f32 v72, v72, s75, v73
	v_pk_mul_f32 v[68:69], v[68:69], v[80:81] op_sel_hi:[1,0]
	v_max_f32_e32 v73, v70, v71
	v_pk_mul_f32 v[80:81], v[64:65], v[80:81] op_sel_hi:[1,0]
	v_max_f32_e32 v64, v66, v67
	v_max3_f32 v73, v68, v69, v73
	v_max3_f32 v64, v80, v81, v64
	v_max3_f32 v64, v72, v73, v64
	v_mov_b32_e32 v65, v64
	s_nop 1
	v_permlane16_swap_b32_e32 v64, v65
	s_waitcnt lgkmcnt(0)
	v_max_f32_e32 v64, v64, v65
	v_mov_b32_e32 v65, v64
	s_nop 1
	v_permlane32_swap_b32_e32 v64, v65
	s_waitcnt lgkmcnt(0)
	v_max_f32_e32 v64, v64, v65
	v_sub_f32_e32 v65, v76, v64
	v_exp_f32_e32 v72, v65
	v_sub_f32_e32 v65, v77, v64
	v_exp_f32_e32 v73, v65
	v_sub_f32_e32 v65, v78, v64
	v_exp_f32_e32 v78, v65
	v_sub_f32_e32 v65, v79, v64
	v_exp_f32_e32 v79, v65
	v_sub_f32_e32 v76, v82, v64
	v_add_f32_e32 v65, 0, v72
	v_exp_f32_e32 v76, v76
	v_sub_f32_e32 v77, v83, v64
	v_add_f32_e32 v65, v73, v65
	v_exp_f32_e32 v77, v77
	v_sub_f32_e32 v74, v74, v64
	v_add_f32_e32 v65, v78, v65
	v_exp_f32_e32 v84, v74
	v_sub_f32_e32 v74, v75, v64
	v_add_f32_e32 v65, v79, v65
	v_exp_f32_e32 v85, v74
	v_sub_f32_e32 v68, v68, v64
	v_add_f32_e32 v65, v76, v65
	v_exp_f32_e32 v74, v68
	v_sub_f32_e32 v68, v69, v64
	v_add_f32_e32 v65, v77, v65
	v_exp_f32_e32 v75, v68
	v_sub_f32_e32 v68, v70, v64
	v_add_f32_e32 v65, v84, v65
	v_exp_f32_e32 v82, v68
	v_sub_f32_e32 v68, v71, v64
	v_add_f32_e32 v65, v85, v65
	v_exp_f32_e32 v83, v68
	v_sub_f32_e32 v68, v80, v64
	v_add_f32_e32 v65, v74, v65
	v_exp_f32_e32 v80, v68
	v_sub_f32_e32 v68, v81, v64
	v_add_f32_e32 v65, v75, v65
	v_exp_f32_e32 v81, v68
	v_sub_f32_e32 v66, v66, v64
	v_add_f32_e32 v65, v82, v65
	v_exp_f32_e32 v86, v66
	v_sub_f32_e32 v66, v67, v64
	v_add_f32_e32 v65, v83, v65
	v_exp_f32_e32 v87, v66
	v_add_f32_e32 v65, v80, v65
	v_add_f32_e32 v65, v81, v65
	v_add_f32_e32 v65, v86, v65
	v_add_f32_e32 v65, v87, v65
	v_mov_b32_e32 v66, v65
	s_nop 1
	v_permlane16_swap_b32_e32 v65, v66
	s_waitcnt lgkmcnt(0)
	v_add_f32_e32 v65, v65, v66
	v_mov_b32_e32 v66, v65
	s_nop 1
	v_permlane32_swap_b32_e32 v65, v66
	s_and_saveexec_b64 s[2:3], s[6:7]
	s_cbranch_execz .LBB0_590
	s_waitcnt lgkmcnt(0)
	v_add_f32_e32 v65, v65, v66
	v_add_u32_e32 v66, s67, v167
	ds_write_b64 v66, v[64:65]
;     __device__ __forceinline__ void operator()(Acc& acc, const Unit& u, int wr, int wc, int fr, int fq, PG8_LAS unsigned char* xl) const {
;     ...
;             for (int m = 0; m < 4; ++m) { const int rl = ai * HALF + wr * 64 + m * 16 + fr; const float rs = S[rl];
;                 float mx = -INFINITY;
; #pragma unroll
;                 for (int bj = 0; bj < 2; ++bj)
; #pragma unroll
;                     for (int n = 0; n < 2; ++n) { const f32x4 v = acc[ai][bj][m][n] * rs; acc[ai][bj][m][n] = v; mx = fmaxf(mx, fmaxf(fmaxf(v[0], v[1]), fmaxf(v[2], v[3]))); }
;                 mx = fmaxf(mx, __shfl_xor(mx, 16)); mx = fmaxf(mx, __shfl_xor(mx, 32));
;                 float s = 0.f;
; #pragma unroll
;                 for (int bj = 0; bj < 2; ++bj)
; #pragma unroll
;                     for (int n = 0; n < 2; ++n) { f32x4 v = acc[ai][bj][m][n];
; #pragma unroll
;                         for (int e = 0; e < 4; ++e) { v[e] = __builtin_amdgcn_exp2f(v[e] - mx); s += v[e]; }
;                         acc[ai][bj][m][n] = v; }
;                 s += __shfl_xor(s, 16); s += __shfl_xor(s, 32);
;                 if (fq == 0) X[rl * 4 + wc] = (f32x2){mx, s};
.LBB0_590:
	s_or_b64 exec, exec, s[2:3]
	ds_read_b32 v64, v169
	s_waitcnt lgkmcnt(0)
	v_pk_mul_f32 v[62:63], v[62:63], v[64:65] op_sel_hi:[1,0]
	v_pk_mul_f32 v[58:59], v[58:59], v[64:65] op_sel_hi:[1,0]
	v_pk_mul_f32 v[60:61], v[60:61], v[64:65] op_sel_hi:[1,0]
	v_pk_mul_f32 v[66:67], v[56:57], v[64:65] op_sel_hi:[1,0]
	v_max_f32_e32 v56, v62, v63
	v_max_f32_e32 v57, v58, v59
	v_max3_f32 v56, v60, v61, v56
	v_max3_f32 v57, v66, v67, v57
	v_pk_mul_f32 v[54:55], v[54:55], v[64:65] op_sel_hi:[1,0]
	v_pk_mul_f32 v[50:51], v[50:51], v[64:65] op_sel_hi:[1,0]
	v_max3_f32 v56, v56, s75, v57
	v_pk_mul_f32 v[52:53], v[52:53], v[64:65] op_sel_hi:[1,0]
	v_max_f32_e32 v57, v54, v55
	v_pk_mul_f32 v[64:65], v[48:49], v[64:65] op_sel_hi:[1,0]
	v_max_f32_e32 v48, v50, v51
	v_max3_f32 v57, v52, v53, v57
	v_max3_f32 v48, v64, v65, v48
	v_max3_f32 v48, v56, v57, v48
	v_mov_b32_e32 v49, v48
	s_nop 1
	v_permlane16_swap_b32_e32 v48, v49
	s_waitcnt lgkmcnt(0)
	v_max_f32_e32 v48, v48, v49
	v_mov_b32_e32 v49, v48
	s_nop 1
	v_permlane32_swap_b32_e32 v48, v49
	s_waitcnt lgkmcnt(0)
	v_max_f32_e32 v48, v48, v49
	v_sub_f32_e32 v49, v60, v48
	v_exp_f32_e32 v56, v49
	v_sub_f32_e32 v49, v61, v48
	v_exp_f32_e32 v57, v49
	v_sub_f32_e32 v49, v62, v48
	v_exp_f32_e32 v62, v49
	v_sub_f32_e32 v49, v63, v48
	v_exp_f32_e32 v63, v49
	v_sub_f32_e32 v60, v66, v48
	v_add_f32_e32 v49, 0, v56
	v_exp_f32_e32 v60, v60
	v_sub_f32_e32 v61, v67, v48
	v_add_f32_e32 v49, v57, v49
	v_exp_f32_e32 v61, v61
	v_sub_f32_e32 v58, v58, v48
	v_add_f32_e32 v49, v62, v49
	v_exp_f32_e32 v68, v58
	v_sub_f32_e32 v58, v59, v48
	v_add_f32_e32 v49, v63, v49
	v_exp_f32_e32 v69, v58
	v_sub_f32_e32 v52, v52, v48
	v_add_f32_e32 v49, v60, v49
	v_exp_f32_e32 v58, v52
	v_sub_f32_e32 v52, v53, v48
	v_add_f32_e32 v49, v61, v49
	v_exp_f32_e32 v59, v52
	v_sub_f32_e32 v52, v54, v48
	v_add_f32_e32 v49, v68, v49
	v_exp_f32_e32 v66, v52
	v_sub_f32_e32 v52, v55, v48
	v_add_f32_e32 v49, v69, v49
	v_exp_f32_e32 v67, v52
	v_sub_f32_e32 v52, v64, v48
	v_add_f32_e32 v49, v58, v49
	v_exp_f32_e32 v64, v52
	v_sub_f32_e32 v52, v65, v48
	v_add_f32_e32 v49, v59, v49
	v_exp_f32_e32 v65, v52
	v_sub_f32_e32 v50, v50, v48
	v_add_f32_e32 v49, v66, v49
	v_exp_f32_e32 v70, v50
	v_sub_f32_e32 v50, v51, v48
	v_add_f32_e32 v49, v67, v49
	v_exp_f32_e32 v71, v50
	v_add_f32_e32 v49, v64, v49
	v_add_f32_e32 v49, v65, v49
	v_add_f32_e32 v49, v70, v49
	v_add_f32_e32 v49, v71, v49
	v_mov_b32_e32 v50, v49
	s_nop 1
	v_permlane16_swap_b32_e32 v49, v50
	s_waitcnt lgkmcnt(0)
	v_add_f32_e32 v49, v49, v50
	v_mov_b32_e32 v50, v49
	s_nop 1
	v_permlane32_swap_b32_e32 v49, v50
	s_and_saveexec_b64 s[2:3], s[6:7]
	s_cbranch_execz .LBB0_592
	s_waitcnt lgkmcnt(0)
	v_add_f32_e32 v49, v49, v50
	v_add_u32_e32 v50, s67, v170
	ds_write_b64 v50, v[48:49]
.LBB0_592:
	s_or_b64 exec, exec, s[2:3]
	ds_read_b32 v48, v172
	s_waitcnt lgkmcnt(0)
	v_pk_mul_f32 v[46:47], v[46:47], v[48:49] op_sel_hi:[1,0]
	v_pk_mul_f32 v[42:43], v[42:43], v[48:49] op_sel_hi:[1,0]
	v_pk_mul_f32 v[44:45], v[44:45], v[48:49] op_sel_hi:[1,0]
	v_pk_mul_f32 v[50:51], v[40:41], v[48:49] op_sel_hi:[1,0]
	v_max_f32_e32 v40, v46, v47
	v_max_f32_e32 v41, v42, v43
	v_max3_f32 v40, v44, v45, v40
	v_max3_f32 v41, v50, v51, v41
	v_pk_mul_f32 v[38:39], v[38:39], v[48:49] op_sel_hi:[1,0]
	v_pk_mul_f32 v[34:35], v[34:35], v[48:49] op_sel_hi:[1,0]
	v_max3_f32 v40, v40, s75, v41
	v_pk_mul_f32 v[36:37], v[36:37], v[48:49] op_sel_hi:[1,0]
	v_max_f32_e32 v41, v38, v39
	v_pk_mul_f32 v[48:49], v[32:33], v[48:49] op_sel_hi:[1,0]
	v_max_f32_e32 v32, v34, v35
	v_max3_f32 v41, v36, v37, v41
	v_max3_f32 v32, v48, v49, v32
	v_max3_f32 v32, v40, v41, v32
	v_mov_b32_e32 v33, v32
	s_nop 1
	v_permlane16_swap_b32_e32 v32, v33
	s_waitcnt lgkmcnt(0)
	v_max_f32_e32 v32, v32, v33
	v_mov_b32_e32 v33, v32
	s_nop 1
	v_permlane32_swap_b32_e32 v32, v33
	s_waitcnt lgkmcnt(0)
	v_max_f32_e32 v32, v32, v33
	v_sub_f32_e32 v33, v44, v32
	v_exp_f32_e32 v40, v33
	v_sub_f32_e32 v33, v45, v32
	v_exp_f32_e32 v41, v33
	v_sub_f32_e32 v33, v46, v32
	v_exp_f32_e32 v46, v33
	v_sub_f32_e32 v33, v47, v32
	v_exp_f32_e32 v47, v33
	v_sub_f32_e32 v44, v50, v32
	v_add_f32_e32 v33, 0, v40
	v_exp_f32_e32 v44, v44
	v_sub_f32_e32 v45, v51, v32
	v_add_f32_e32 v33, v41, v33
	v_exp_f32_e32 v45, v45
	v_sub_f32_e32 v42, v42, v32
	v_add_f32_e32 v33, v46, v33
	v_exp_f32_e32 v52, v42
	v_sub_f32_e32 v42, v43, v32
	v_add_f32_e32 v33, v47, v33
	v_exp_f32_e32 v53, v42
	v_sub_f32_e32 v36, v36, v32
	v_add_f32_e32 v33, v44, v33
	v_exp_f32_e32 v42, v36
	v_sub_f32_e32 v36, v37, v32
	v_add_f32_e32 v33, v45, v33
	v_exp_f32_e32 v43, v36
	v_sub_f32_e32 v36, v38, v32
	v_add_f32_e32 v33, v52, v33
	v_exp_f32_e32 v50, v36
	v_sub_f32_e32 v36, v39, v32
	v_add_f32_e32 v33, v53, v33
	v_exp_f32_e32 v51, v36
	v_sub_f32_e32 v36, v48, v32
	v_add_f32_e32 v33, v42, v33
	v_exp_f32_e32 v48, v36
	v_sub_f32_e32 v36, v49, v32
	v_add_f32_e32 v33, v43, v33
	v_exp_f32_e32 v49, v36
	v_sub_f32_e32 v34, v34, v32
	v_add_f32_e32 v33, v50, v33
	v_exp_f32_e32 v54, v34
	v_sub_f32_e32 v34, v35, v32
	v_add_f32_e32 v33, v51, v33
	v_exp_f32_e32 v55, v34
	v_add_f32_e32 v33, v48, v33
	v_add_f32_e32 v33, v49, v33
	v_add_f32_e32 v33, v54, v33
	v_add_f32_e32 v33, v55, v33
	v_mov_b32_e32 v34, v33
	s_nop 1
	v_permlane16_swap_b32_e32 v33, v34
	s_waitcnt lgkmcnt(0)
	v_add_f32_e32 v33, v33, v34
	v_mov_b32_e32 v34, v33
	s_nop 1
	v_permlane32_swap_b32_e32 v33, v34
	s_and_saveexec_b64 s[2:3], s[6:7]
	s_cbranch_execz .LBB0_594
	s_waitcnt lgkmcnt(0)
	v_add_f32_e32 v33, v33, v34
	v_add_u32_e32 v34, s67, v173
	ds_write_b64 v34, v[32:33]
;     __device__ __forceinline__ void operator()(Acc& acc, const Unit& u, int wr, int wc, int fr, int fq, PG8_LAS unsigned char* xl) const {
;     ...
;             for (int m = 0; m < 4; ++m) { const int rl = ai * HALF + wr * 64 + m * 16 + fr; const float rs = S[rl];
;                 float mx = -INFINITY;
; #pragma unroll
;                 for (int bj = 0; bj < 2; ++bj)
; #pragma unroll
;                     for (int n = 0; n < 2; ++n) { const f32x4 v = acc[ai][bj][m][n] * rs; acc[ai][bj][m][n] = v; mx = fmaxf(mx, fmaxf(fmaxf(v[0], v[1]), fmaxf(v[2], v[3]))); }
;                 mx = fmaxf(mx, __shfl_xor(mx, 16)); mx = fmaxf(mx, __shfl_xor(mx, 32));
;                 float s = 0.f;
; #pragma unroll
;                 for (int bj = 0; bj < 2; ++bj)
; #pragma unroll
;                     for (int n = 0; n < 2; ++n) { f32x4 v = acc[ai][bj][m][n];
; #pragma unroll
;                         for (int e = 0; e < 4; ++e) { v[e] = __builtin_amdgcn_exp2f(v[e] - mx); s += v[e]; }
;                         acc[ai][bj][m][n] = v; }
;                 s += __shfl_xor(s, 16); s += __shfl_xor(s, 32);
;                 if (fq == 0) X[rl * 4 + wc] = (f32x2){mx, s};
.LBB0_594:
	s_or_b64 exec, exec, s[2:3]
	ds_read_b32 v32, v175
	s_waitcnt lgkmcnt(0)
	v_pk_mul_f32 v[30:31], v[30:31], v[32:33] op_sel_hi:[1,0]
	v_pk_mul_f32 v[26:27], v[26:27], v[32:33] op_sel_hi:[1,0]
	v_pk_mul_f32 v[28:29], v[28:29], v[32:33] op_sel_hi:[1,0]
	v_pk_mul_f32 v[34:35], v[24:25], v[32:33] op_sel_hi:[1,0]
	v_max_f32_e32 v24, v30, v31
	v_max_f32_e32 v25, v26, v27
	v_max3_f32 v24, v28, v29, v24
	v_max3_f32 v25, v34, v35, v25
	v_pk_mul_f32 v[22:23], v[22:23], v[32:33] op_sel_hi:[1,0]
	v_pk_mul_f32 v[18:19], v[18:19], v[32:33] op_sel_hi:[1,0]
	v_max3_f32 v24, v24, s75, v25
	v_pk_mul_f32 v[20:21], v[20:21], v[32:33] op_sel_hi:[1,0]
	v_max_f32_e32 v25, v22, v23
	v_pk_mul_f32 v[32:33], v[16:17], v[32:33] op_sel_hi:[1,0]
	v_max_f32_e32 v16, v18, v19
	v_max3_f32 v25, v20, v21, v25
	v_max3_f32 v16, v32, v33, v16
	v_max3_f32 v16, v24, v25, v16
	v_mov_b32_e32 v17, v16
	s_nop 1
	v_permlane16_swap_b32_e32 v16, v17
	s_waitcnt lgkmcnt(0)
	v_max_f32_e32 v16, v16, v17
	v_mov_b32_e32 v17, v16
	s_nop 1
	v_permlane32_swap_b32_e32 v16, v17
	s_waitcnt lgkmcnt(0)
	v_max_f32_e32 v16, v16, v17
	v_sub_f32_e32 v17, v28, v16
	v_exp_f32_e32 v24, v17
	v_sub_f32_e32 v17, v29, v16
	v_exp_f32_e32 v25, v17
	v_sub_f32_e32 v17, v30, v16
	v_exp_f32_e32 v30, v17
	v_sub_f32_e32 v17, v31, v16
	v_exp_f32_e32 v31, v17
	v_sub_f32_e32 v28, v34, v16
	v_add_f32_e32 v17, 0, v24
	v_exp_f32_e32 v28, v28
	v_sub_f32_e32 v29, v35, v16
	v_add_f32_e32 v17, v25, v17
	v_exp_f32_e32 v29, v29
	v_sub_f32_e32 v26, v26, v16
	v_add_f32_e32 v17, v30, v17
	v_exp_f32_e32 v36, v26
	v_sub_f32_e32 v26, v27, v16
	v_add_f32_e32 v17, v31, v17
	v_exp_f32_e32 v37, v26
	v_sub_f32_e32 v20, v20, v16
	v_add_f32_e32 v17, v28, v17
	v_exp_f32_e32 v26, v20
	v_sub_f32_e32 v20, v21, v16
	v_add_f32_e32 v17, v29, v17
	v_exp_f32_e32 v27, v20
	v_sub_f32_e32 v20, v22, v16
	v_add_f32_e32 v17, v36, v17
	v_exp_f32_e32 v34, v20
	v_sub_f32_e32 v20, v23, v16
	v_add_f32_e32 v17, v37, v17
	v_exp_f32_e32 v35, v20
	v_sub_f32_e32 v20, v32, v16
	v_add_f32_e32 v17, v26, v17
	v_exp_f32_e32 v32, v20
	v_sub_f32_e32 v20, v33, v16
	v_add_f32_e32 v17, v27, v17
	v_exp_f32_e32 v33, v20
	v_sub_f32_e32 v18, v18, v16
	v_add_f32_e32 v17, v34, v17
	v_exp_f32_e32 v38, v18
	v_sub_f32_e32 v18, v19, v16
	v_add_f32_e32 v17, v35, v17
	v_exp_f32_e32 v39, v18
	v_add_f32_e32 v17, v32, v17
	v_add_f32_e32 v17, v33, v17
	v_add_f32_e32 v17, v38, v17
	v_add_f32_e32 v17, v39, v17
	v_mov_b32_e32 v18, v17
	s_nop 1
	v_permlane16_swap_b32_e32 v17, v18
	s_waitcnt lgkmcnt(0)
	v_add_f32_e32 v17, v17, v18
	v_mov_b32_e32 v18, v17
	s_nop 1
	v_permlane32_swap_b32_e32 v17, v18
	s_and_saveexec_b64 s[2:3], s[6:7]
	s_cbranch_execz .LBB0_596
	s_waitcnt lgkmcnt(0)
	v_add_f32_e32 v17, v17, v18
	v_add_u32_e32 v18, s67, v176
	ds_write_b64 v18, v[16:17]
.LBB0_596:
	s_or_b64 exec, exec, s[2:3]
	ds_read_b32 v16, v179
	s_waitcnt lgkmcnt(0)
	v_pk_mul_f32 v[14:15], v[14:15], v[16:17] op_sel_hi:[1,0]
	v_pk_mul_f32 v[10:11], v[10:11], v[16:17] op_sel_hi:[1,0]
	v_pk_mul_f32 v[12:13], v[12:13], v[16:17] op_sel_hi:[1,0]
	v_pk_mul_f32 v[18:19], v[8:9], v[16:17] op_sel_hi:[1,0]
	v_max_f32_e32 v8, v14, v15
	v_max_f32_e32 v9, v10, v11
	v_max3_f32 v8, v12, v13, v8
	v_max3_f32 v9, v18, v19, v9
	v_pk_mul_f32 v[6:7], v[6:7], v[16:17] op_sel_hi:[1,0]
	v_pk_mul_f32 v[2:3], v[2:3], v[16:17] op_sel_hi:[1,0]
	v_max3_f32 v8, v8, s75, v9
	v_pk_mul_f32 v[4:5], v[4:5], v[16:17] op_sel_hi:[1,0]
	v_max_f32_e32 v9, v6, v7
	v_pk_mul_f32 v[16:17], v[0:1], v[16:17] op_sel_hi:[1,0]
	v_max_f32_e32 v0, v2, v3
	v_max3_f32 v9, v4, v5, v9
	v_max3_f32 v0, v16, v17, v0
	v_max3_f32 v0, v8, v9, v0
	v_mov_b32_e32 v1, v0
	s_nop 1
	v_permlane16_swap_b32_e32 v0, v1
	s_waitcnt lgkmcnt(0)
	v_max_f32_e32 v0, v0, v1
	v_mov_b32_e32 v1, v0
	s_nop 1
	v_permlane32_swap_b32_e32 v0, v1
	s_waitcnt lgkmcnt(0)
	v_max_f32_e32 v0, v0, v1
	v_sub_f32_e32 v1, v12, v0
	v_exp_f32_e32 v8, v1
	v_sub_f32_e32 v1, v13, v0
	v_exp_f32_e32 v9, v1
	v_sub_f32_e32 v1, v14, v0
	v_exp_f32_e32 v14, v1
	v_sub_f32_e32 v1, v15, v0
	v_exp_f32_e32 v15, v1
	v_sub_f32_e32 v12, v18, v0
	v_add_f32_e32 v1, 0, v8
	v_exp_f32_e32 v12, v12
	v_sub_f32_e32 v13, v19, v0
	v_add_f32_e32 v1, v9, v1
	v_exp_f32_e32 v13, v13
	v_sub_f32_e32 v10, v10, v0
	v_add_f32_e32 v1, v14, v1
	v_exp_f32_e32 v20, v10
	v_sub_f32_e32 v10, v11, v0
	v_add_f32_e32 v1, v15, v1
	v_exp_f32_e32 v21, v10
	v_sub_f32_e32 v4, v4, v0
	v_add_f32_e32 v1, v12, v1
	v_exp_f32_e32 v10, v4
	v_sub_f32_e32 v4, v5, v0
	v_add_f32_e32 v1, v13, v1
	v_exp_f32_e32 v11, v4
	v_sub_f32_e32 v4, v6, v0
	v_add_f32_e32 v1, v20, v1
	v_exp_f32_e32 v18, v4
	v_sub_f32_e32 v4, v7, v0
	v_add_f32_e32 v1, v21, v1
	v_exp_f32_e32 v19, v4
	v_sub_f32_e32 v4, v16, v0
	v_add_f32_e32 v1, v10, v1
	v_exp_f32_e32 v16, v4
	v_sub_f32_e32 v4, v17, v0
	v_add_f32_e32 v1, v11, v1
	v_exp_f32_e32 v17, v4
	v_sub_f32_e32 v2, v2, v0
	v_add_f32_e32 v1, v18, v1
	v_exp_f32_e32 v22, v2
	v_sub_f32_e32 v2, v3, v0
	v_add_f32_e32 v1, v19, v1
	v_exp_f32_e32 v23, v2
	v_add_f32_e32 v1, v16, v1
	v_add_f32_e32 v1, v17, v1
	v_add_f32_e32 v1, v22, v1
	v_add_f32_e32 v1, v23, v1
	v_mov_b32_e32 v2, v1
	s_nop 1
	v_permlane16_swap_b32_e32 v1, v2
	s_waitcnt lgkmcnt(0)
	v_add_f32_e32 v1, v1, v2
	v_mov_b32_e32 v2, v1
	s_nop 1
	v_permlane32_swap_b32_e32 v1, v2
	s_and_saveexec_b64 s[2:3], s[6:7]
	s_cbranch_execz .LBB0_598
	s_waitcnt lgkmcnt(0)
	v_add_f32_e32 v1, v1, v2
	v_add_u32_e32 v2, s67, v180
	ds_write_b64 v2, v[0:1]
